# LDS-DMA attention loop with two alternating f32 row-sum accumulators (shorter dependent add chains), summed in the finalize
# speedup vs baseline: 1.0034x; 1.0034x over previous
.Lattn_nf_loop:
	ds_read_b128 v[98:101], v82 offset:0
	ds_read_b128 v[102:105], v83 offset:0
	ds_read_b128 v[106:109], v84 offset:0
	ds_read_b128 v[110:113], v85 offset:0
	s_and_b32 s10, s15, 1
	s_xor_b32 s10, s10, 1
	s_lshl_b32 s10, s10, 15
	s_add_i32 s10, s10, s11
	s_add_i32 s6, s10, 0x10000
	s_waitcnt lgkmcnt(3)
	v_mfma_f32_32x32x16_bf16 v[138:153], v[98:101], v[10:13], 0
	ds_read_b128 v[98:101], v82 offset:8192
	s_add_i32 m0, s10, 0x0
	s_nop 0
	global_load_lds_dwordx4 v124, s[64:65]
	s_waitcnt lgkmcnt(3)
	v_mfma_f32_32x32x16_bf16 v[138:153], v[102:105], v[14:17], v[138:153]
	ds_read_b128 v[102:105], v83 offset:8192
	s_add_i32 m0, s10, 0x2000
	s_nop 0
	global_load_lds_dwordx4 v124, s[66:67]
	s_waitcnt lgkmcnt(3)
	v_mfma_f32_32x32x16_bf16 v[138:153], v[106:109], v[2:5], v[138:153]
	ds_read_b128 v[106:109], v84 offset:8192
	s_add_i32 m0, s10, 0x4000
	s_nop 0
	global_load_lds_dwordx4 v124, s[68:69]
	s_waitcnt lgkmcnt(3)
	v_mfma_f32_32x32x16_bf16 v[138:153], v[110:113], v[6:9], v[138:153]
	ds_read_b128 v[110:113], v85 offset:8192
	s_add_i32 m0, s10, 0x6000
	s_nop 0
	global_load_lds_dwordx4 v124, s[70:71]
	v_add_u32_e32 v124, s36, v124
	s_waitcnt lgkmcnt(3)
	v_mfma_f32_32x32x16_bf16 v[154:169], v[98:101], v[10:13], 0
	ds_read_b128 v[98:101], v82 offset:16384
	s_add_i32 m0, s6, 0x0
	s_nop 0
	global_load_lds_dwordx4 v125, s[72:73]
	ds_read_b128 v[128:131], v86 offset:0
	ds_read_b128 v[184:187], v86 offset:8192
	v_exp_f32_e32 v138, v138
	v_exp_f32_e32 v139, v139
	v_exp_f32_e32 v140, v140
	v_exp_f32_e32 v141, v141
	v_exp_f32_e32 v142, v142
	v_exp_f32_e32 v143, v143
	s_waitcnt lgkmcnt(5)
	v_mfma_f32_32x32x16_bf16 v[154:169], v[102:105], v[14:17], v[154:169]
	ds_read_b128 v[102:105], v83 offset:16384
	s_add_i32 m0, s6, 0x2000
	s_nop 0
	global_load_lds_dwordx4 v125, s[74:75]
	ds_read_b128 v[188:191], v86 offset:16384
	ds_read_b128 v[192:195], v86 offset:24576
	v_exp_f32_e32 v144, v144
	v_exp_f32_e32 v145, v145
	v_add_f32_e32 v122, v138, v122
	v_add_f32_e32 v123, v139, v123
	v_add_f32_e32 v122, v140, v122
	v_add_f32_e32 v123, v141, v123
	v_add_f32_e32 v122, v142, v122
	v_add_f32_e32 v123, v143, v123
	v_add_f32_e32 v122, v144, v122
	v_add_f32_e32 v123, v145, v123
	v_cvt_pk_bf16_f32 v114, v138, v139
	v_cvt_pk_bf16_f32 v115, v140, v141
	v_cvt_pk_bf16_f32 v116, v142, v143
	v_cvt_pk_bf16_f32 v117, v144, v145
	s_waitcnt lgkmcnt(7)
	v_mfma_f32_32x32x16_bf16 v[154:169], v[106:109], v[2:5], v[154:169]
	ds_read_b128 v[106:109], v84 offset:16384
	s_add_i32 m0, s6, 0x4000
	s_nop 0
	global_load_lds_dwordx4 v125, s[76:77]
	ds_read_b128 v[196:199], v87 offset:0
	v_exp_f32_e32 v146, v146
	v_exp_f32_e32 v147, v147
	s_waitcnt lgkmcnt(8)
	v_mfma_f32_32x32x16_bf16 v[154:169], v[110:113], v[6:9], v[154:169]
	ds_read_b128 v[110:113], v85 offset:16384
	s_add_i32 m0, s6, 0x6000
	s_nop 0
	global_load_lds_dwordx4 v125, s[78:79]
	v_add_u32_e32 v125, s38, v125
	ds_read_b128 v[216:219], v87 offset:8192
	v_exp_f32_e32 v148, v148
	v_exp_f32_e32 v149, v149
	s_waitcnt lgkmcnt(8)
	v_mfma_f32_32x32x16_bf16 v[18:33], v[128:131], v[114:117], v[18:33]
	v_exp_f32_e32 v150, v150
	v_exp_f32_e32 v151, v151
	s_waitcnt lgkmcnt(7)
	v_mfma_f32_32x32x16_bf16 v[34:49], v[184:187], v[114:117], v[34:49]
	ds_read_b128 v[200:203], v87 offset:16384
	v_exp_f32_e32 v152, v152
	v_exp_f32_e32 v153, v153
	s_waitcnt lgkmcnt(6)
	v_mfma_f32_32x32x16_bf16 v[50:65], v[188:191], v[114:117], v[50:65]
	ds_read_b128 v[204:207], v87 offset:24576
	v_add_f32_e32 v122, v146, v122
	v_add_f32_e32 v123, v147, v123
	v_add_f32_e32 v122, v148, v122
	v_add_f32_e32 v123, v149, v123
	s_waitcnt lgkmcnt(6)
	v_mfma_f32_32x32x16_bf16 v[66:81], v[192:195], v[114:117], v[66:81]
	v_add_f32_e32 v122, v150, v122
	v_add_f32_e32 v123, v151, v123
	v_add_f32_e32 v122, v152, v122
	v_add_f32_e32 v123, v153, v123
	v_cvt_pk_bf16_f32 v118, v146, v147
	v_cvt_pk_bf16_f32 v119, v148, v149
	v_cvt_pk_bf16_f32 v120, v150, v151
	v_cvt_pk_bf16_f32 v121, v152, v153
	v_mfma_f32_32x32x16_bf16 v[138:153], v[98:101], v[10:13], 0
	ds_read_b128 v[98:101], v82 offset:24576
	ds_read_b128 v[128:131], v88 offset:0
	v_exp_f32_e32 v154, v154
	v_exp_f32_e32 v155, v155
	v_mfma_f32_32x32x16_bf16 v[138:153], v[102:105], v[14:17], v[138:153]
	ds_read_b128 v[102:105], v83 offset:24576
	ds_read_b128 v[184:187], v88 offset:8192
	v_exp_f32_e32 v156, v156
	v_exp_f32_e32 v157, v157
	s_waitcnt lgkmcnt(8)
	v_mfma_f32_32x32x16_bf16 v[18:33], v[196:199], v[118:121], v[18:33]
	v_exp_f32_e32 v158, v158
	v_exp_f32_e32 v159, v159
	s_waitcnt lgkmcnt(6)
	v_mfma_f32_32x32x16_bf16 v[34:49], v[216:219], v[118:121], v[34:49]
	ds_read_b128 v[188:191], v88 offset:16384
	v_exp_f32_e32 v160, v160
	v_exp_f32_e32 v161, v161
	s_waitcnt lgkmcnt(6)
	v_mfma_f32_32x32x16_bf16 v[50:65], v[200:203], v[118:121], v[50:65]
	ds_read_b128 v[192:195], v88 offset:24576
	v_add_f32_e32 v122, v154, v122
	v_add_f32_e32 v123, v155, v123
	v_add_f32_e32 v122, v156, v122
	v_add_f32_e32 v123, v157, v123
	s_waitcnt lgkmcnt(6)
	v_mfma_f32_32x32x16_bf16 v[66:81], v[204:207], v[118:121], v[66:81]
	v_add_f32_e32 v122, v158, v122
	v_add_f32_e32 v123, v159, v123
	v_add_f32_e32 v122, v160, v122
	v_add_f32_e32 v123, v161, v123
	v_cvt_pk_bf16_f32 v114, v154, v155
	v_cvt_pk_bf16_f32 v115, v156, v157
	v_cvt_pk_bf16_f32 v116, v158, v159
	v_cvt_pk_bf16_f32 v117, v160, v161
	v_mfma_f32_32x32x16_bf16 v[138:153], v[106:109], v[2:5], v[138:153]
	ds_read_b128 v[106:109], v84 offset:24576
	ds_read_b128 v[196:199], v89 offset:0
	v_exp_f32_e32 v162, v162
	v_exp_f32_e32 v163, v163
	v_mfma_f32_32x32x16_bf16 v[138:153], v[110:113], v[6:9], v[138:153]
	ds_read_b128 v[110:113], v85 offset:24576
	ds_read_b128 v[216:219], v89 offset:8192
	v_exp_f32_e32 v164, v164
	v_exp_f32_e32 v165, v165
	s_waitcnt lgkmcnt(8)
	v_mfma_f32_32x32x16_bf16 v[18:33], v[128:131], v[114:117], v[18:33]
	v_exp_f32_e32 v166, v166
	v_exp_f32_e32 v167, v167
	s_waitcnt lgkmcnt(6)
	v_mfma_f32_32x32x16_bf16 v[34:49], v[184:187], v[114:117], v[34:49]
	ds_read_b128 v[200:203], v89 offset:16384
	v_exp_f32_e32 v168, v168
	v_exp_f32_e32 v169, v169
	s_waitcnt lgkmcnt(6)
	v_mfma_f32_32x32x16_bf16 v[50:65], v[188:191], v[114:117], v[50:65]
	ds_read_b128 v[204:207], v89 offset:24576
	v_add_f32_e32 v122, v162, v122
	v_add_f32_e32 v123, v163, v123
	v_add_f32_e32 v122, v164, v122
	v_add_f32_e32 v123, v165, v123
	s_waitcnt lgkmcnt(6)
	v_mfma_f32_32x32x16_bf16 v[66:81], v[192:195], v[114:117], v[66:81]
	v_add_f32_e32 v122, v166, v122
	v_add_f32_e32 v123, v167, v123
	v_add_f32_e32 v122, v168, v122
	v_add_f32_e32 v123, v169, v123
	v_cvt_pk_bf16_f32 v118, v162, v163
	v_cvt_pk_bf16_f32 v119, v164, v165
	v_cvt_pk_bf16_f32 v120, v166, v167
	v_cvt_pk_bf16_f32 v121, v168, v169
	v_mfma_f32_32x32x16_bf16 v[154:169], v[98:101], v[10:13], 0
	ds_read_b128 v[128:131], v90 offset:0
	v_exp_f32_e32 v138, v138
	v_exp_f32_e32 v139, v139
	v_mfma_f32_32x32x16_bf16 v[154:169], v[102:105], v[14:17], v[154:169]
	ds_read_b128 v[184:187], v90 offset:8192
	v_exp_f32_e32 v140, v140
	v_exp_f32_e32 v141, v141
	s_waitcnt lgkmcnt(6)
	v_mfma_f32_32x32x16_bf16 v[18:33], v[196:199], v[118:121], v[18:33]
	v_exp_f32_e32 v142, v142
	v_exp_f32_e32 v143, v143
	s_waitcnt lgkmcnt(4)
	v_mfma_f32_32x32x16_bf16 v[34:49], v[216:219], v[118:121], v[34:49]
	ds_read_b128 v[188:191], v90 offset:16384
	v_exp_f32_e32 v144, v144
	v_exp_f32_e32 v145, v145
	s_waitcnt lgkmcnt(4)
	v_mfma_f32_32x32x16_bf16 v[50:65], v[200:203], v[118:121], v[50:65]
	ds_read_b128 v[192:195], v90 offset:24576
	v_add_f32_e32 v122, v138, v122
	v_add_f32_e32 v123, v139, v123
	v_add_f32_e32 v122, v140, v122
	v_add_f32_e32 v123, v141, v123
	s_waitcnt lgkmcnt(4)
	v_mfma_f32_32x32x16_bf16 v[66:81], v[204:207], v[118:121], v[66:81]
	v_add_f32_e32 v122, v142, v122
	v_add_f32_e32 v123, v143, v123
	v_add_f32_e32 v122, v144, v122
	v_add_f32_e32 v123, v145, v123
	v_cvt_pk_bf16_f32 v114, v138, v139
	v_cvt_pk_bf16_f32 v115, v140, v141
	v_cvt_pk_bf16_f32 v116, v142, v143
	v_cvt_pk_bf16_f32 v117, v144, v145
	v_mfma_f32_32x32x16_bf16 v[154:169], v[106:109], v[2:5], v[154:169]
	ds_read_b128 v[196:199], v91 offset:0
	v_exp_f32_e32 v146, v146
	v_exp_f32_e32 v147, v147
	v_mfma_f32_32x32x16_bf16 v[154:169], v[110:113], v[6:9], v[154:169]
	ds_read_b128 v[216:219], v91 offset:8192
	v_exp_f32_e32 v148, v148
	v_exp_f32_e32 v149, v149
	s_waitcnt lgkmcnt(5)
	v_mfma_f32_32x32x16_bf16 v[18:33], v[128:131], v[114:117], v[18:33]
	v_exp_f32_e32 v150, v150
	v_exp_f32_e32 v151, v151
	s_waitcnt lgkmcnt(4)
	v_mfma_f32_32x32x16_bf16 v[34:49], v[184:187], v[114:117], v[34:49]
	ds_read_b128 v[200:203], v91 offset:16384
	v_exp_f32_e32 v152, v152
	v_exp_f32_e32 v153, v153
	s_waitcnt lgkmcnt(4)
	v_mfma_f32_32x32x16_bf16 v[50:65], v[188:191], v[114:117], v[50:65]
	ds_read_b128 v[204:207], v91 offset:24576
	v_add_f32_e32 v122, v146, v122
	v_add_f32_e32 v123, v147, v123
	v_add_f32_e32 v122, v148, v122
	v_add_f32_e32 v123, v149, v123
	s_waitcnt lgkmcnt(4)
	v_mfma_f32_32x32x16_bf16 v[66:81], v[192:195], v[114:117], v[66:81]
	v_add_f32_e32 v122, v150, v122
	v_add_f32_e32 v123, v151, v123
	v_add_f32_e32 v122, v152, v122
	v_add_f32_e32 v123, v153, v123
	v_cvt_pk_bf16_f32 v118, v146, v147
	v_cvt_pk_bf16_f32 v119, v148, v149
	v_cvt_pk_bf16_f32 v120, v150, v151
	v_cvt_pk_bf16_f32 v121, v152, v153
	s_waitcnt lgkmcnt(3)
	s_nop 0
	v_mfma_f32_32x32x16_bf16 v[18:33], v[196:199], v[118:121], v[18:33]
	ds_read_b128 v[128:131], v92 offset:0
	v_exp_f32_e32 v154, v154
	v_exp_f32_e32 v155, v155
	v_exp_f32_e32 v156, v156
	s_waitcnt lgkmcnt(3)
	v_mfma_f32_32x32x16_bf16 v[34:49], v[216:219], v[118:121], v[34:49]
	ds_read_b128 v[184:187], v92 offset:8192
	v_exp_f32_e32 v157, v157
	v_exp_f32_e32 v158, v158
	v_exp_f32_e32 v159, v159
	v_exp_f32_e32 v160, v160
	s_waitcnt lgkmcnt(3)
	v_mfma_f32_32x32x16_bf16 v[50:65], v[200:203], v[118:121], v[50:65]
	ds_read_b128 v[188:191], v92 offset:16384
	v_exp_f32_e32 v161, v161
	v_add_f32_e32 v122, v154, v122
	v_add_f32_e32 v123, v155, v123
	v_add_f32_e32 v122, v156, v122
	v_add_f32_e32 v123, v157, v123
	v_add_f32_e32 v122, v158, v122
	s_waitcnt lgkmcnt(3)
	v_mfma_f32_32x32x16_bf16 v[66:81], v[204:207], v[118:121], v[66:81]
	ds_read_b128 v[192:195], v92 offset:24576
	v_add_f32_e32 v123, v159, v123
	v_add_f32_e32 v122, v160, v122
	v_add_f32_e32 v123, v161, v123
	v_xor_b32_e32 v82, 0x8000, v82
	v_xor_b32_e32 v83, 0x8000, v83
	v_xor_b32_e32 v84, 0x8000, v84
	v_xor_b32_e32 v85, 0x8000, v85
	v_cvt_pk_bf16_f32 v114, v154, v155
	v_cvt_pk_bf16_f32 v115, v156, v157
	v_cvt_pk_bf16_f32 v116, v158, v159
	v_cvt_pk_bf16_f32 v117, v160, v161
	s_waitcnt lgkmcnt(3)
	s_nop 0
	v_mfma_f32_32x32x16_bf16 v[18:33], v[128:131], v[114:117], v[18:33]
	ds_read_b128 v[196:199], v93 offset:0
	v_exp_f32_e32 v162, v162
	v_exp_f32_e32 v163, v163
	v_exp_f32_e32 v164, v164
	s_waitcnt lgkmcnt(3)
	v_mfma_f32_32x32x16_bf16 v[34:49], v[184:187], v[114:117], v[34:49]
	ds_read_b128 v[216:219], v93 offset:8192
	v_exp_f32_e32 v165, v165
	v_exp_f32_e32 v166, v166
	v_exp_f32_e32 v167, v167
	s_waitcnt lgkmcnt(3)
	v_mfma_f32_32x32x16_bf16 v[50:65], v[188:191], v[114:117], v[50:65]
	ds_read_b128 v[200:203], v93 offset:16384
	v_exp_f32_e32 v168, v168
	v_exp_f32_e32 v169, v169
	v_add_f32_e32 v122, v162, v122
	v_add_f32_e32 v123, v163, v123
	s_waitcnt lgkmcnt(3)
	v_mfma_f32_32x32x16_bf16 v[66:81], v[192:195], v[114:117], v[66:81]
	ds_read_b128 v[204:207], v93 offset:24576
	v_add_f32_e32 v122, v164, v122
	v_add_f32_e32 v123, v165, v123
	v_add_f32_e32 v122, v166, v122
	v_add_f32_e32 v123, v167, v123
	v_add_f32_e32 v122, v168, v122
	v_add_f32_e32 v123, v169, v123
	v_cvt_pk_bf16_f32 v118, v162, v163
	v_cvt_pk_bf16_f32 v119, v164, v165
	v_cvt_pk_bf16_f32 v120, v166, v167
	v_cvt_pk_bf16_f32 v121, v168, v169
	s_waitcnt lgkmcnt(3)
	s_nop 0
	v_mfma_f32_32x32x16_bf16 v[18:33], v[196:199], v[118:121], v[18:33]
	v_xor_b32_e32 v86, 0x8000, v86
	v_xor_b32_e32 v87, 0x8000, v87
	s_waitcnt lgkmcnt(2)
	v_mfma_f32_32x32x16_bf16 v[34:49], v[216:219], v[118:121], v[34:49]
	v_xor_b32_e32 v88, 0x8000, v88
	v_xor_b32_e32 v89, 0x8000, v89
	s_waitcnt lgkmcnt(1)
	v_mfma_f32_32x32x16_bf16 v[50:65], v[200:203], v[118:121], v[50:65]
	v_xor_b32_e32 v90, 0x8000, v90
	v_xor_b32_e32 v91, 0x8000, v91
	s_waitcnt lgkmcnt(0)
	v_mfma_f32_32x32x16_bf16 v[66:81], v[204:207], v[118:121], v[66:81]
	v_xor_b32_e32 v92, 0x8000, v92
	v_xor_b32_e32 v93, 0x8000, v93
	s_waitcnt vmcnt(0)
	s_waitcnt lgkmcnt(0)
	s_barrier
	s_add_i32 s15, s15, 1
	s_cmp_eq_u32 s15, 33
	s_cbranch_scc0 .Lattn_nf_loop
	ds_read_b128 v[98:101], v82 offset:0
	ds_read_b128 v[102:105], v83 offset:0
	ds_read_b128 v[106:109], v84 offset:0
	ds_read_b128 v[110:113], v85 offset:0
	s_waitcnt lgkmcnt(3)
	v_mfma_f32_32x32x16_bf16 v[138:153], v[98:101], v[10:13], 0
	ds_read_b128 v[98:101], v82 offset:8192
	s_waitcnt lgkmcnt(3)
	v_mfma_f32_32x32x16_bf16 v[138:153], v[102:105], v[14:17], v[138:153]
	ds_read_b128 v[102:105], v83 offset:8192
	s_waitcnt lgkmcnt(3)
	v_mfma_f32_32x32x16_bf16 v[138:153], v[106:109], v[2:5], v[138:153]
	ds_read_b128 v[106:109], v84 offset:8192
	s_waitcnt lgkmcnt(3)
	v_mfma_f32_32x32x16_bf16 v[138:153], v[110:113], v[6:9], v[138:153]
	ds_read_b128 v[110:113], v85 offset:8192
	s_waitcnt lgkmcnt(3)
	v_mfma_f32_32x32x16_bf16 v[154:169], v[98:101], v[10:13], 0
	ds_read_b128 v[98:101], v82 offset:16384
	ds_read_b128 v[128:131], v86 offset:0
	ds_read_b128 v[184:187], v86 offset:8192
	s_nop 5
	v_exp_f32_e32 v138, v138
	v_exp_f32_e32 v139, v139
	v_exp_f32_e32 v140, v140
	v_exp_f32_e32 v141, v141
	v_exp_f32_e32 v142, v142
	v_exp_f32_e32 v143, v143
	s_waitcnt lgkmcnt(5)
	v_mfma_f32_32x32x16_bf16 v[154:169], v[102:105], v[14:17], v[154:169]
	ds_read_b128 v[102:105], v83 offset:16384
	ds_read_b128 v[188:191], v86 offset:16384
	ds_read_b128 v[192:195], v86 offset:24576
	v_exp_f32_e32 v144, v144
	v_exp_f32_e32 v145, v145
	v_add_f32_e32 v122, v138, v122
	v_add_f32_e32 v123, v139, v123
	v_add_f32_e32 v122, v140, v122
	v_add_f32_e32 v123, v141, v123
	v_add_f32_e32 v122, v142, v122
	v_add_f32_e32 v123, v143, v123
	v_add_f32_e32 v122, v144, v122
	v_add_f32_e32 v123, v145, v123
	v_cvt_pk_bf16_f32 v114, v138, v139
	v_cvt_pk_bf16_f32 v115, v140, v141
	v_cvt_pk_bf16_f32 v116, v142, v143
	v_cvt_pk_bf16_f32 v117, v144, v145
	s_waitcnt lgkmcnt(7)
	v_mfma_f32_32x32x16_bf16 v[154:169], v[106:109], v[2:5], v[154:169]
	ds_read_b128 v[106:109], v84 offset:16384
	ds_read_b128 v[196:199], v87 offset:0
	v_exp_f32_e32 v146, v146
	v_exp_f32_e32 v147, v147
	s_waitcnt lgkmcnt(8)
	v_mfma_f32_32x32x16_bf16 v[154:169], v[110:113], v[6:9], v[154:169]
	ds_read_b128 v[110:113], v85 offset:16384
	ds_read_b128 v[216:219], v87 offset:8192
	v_exp_f32_e32 v148, v148
	v_exp_f32_e32 v149, v149
	s_waitcnt lgkmcnt(8)
	v_mfma_f32_32x32x16_bf16 v[18:33], v[128:131], v[114:117], v[18:33]
	v_exp_f32_e32 v150, v150
	v_exp_f32_e32 v151, v151
	s_waitcnt lgkmcnt(7)
	v_mfma_f32_32x32x16_bf16 v[34:49], v[184:187], v[114:117], v[34:49]
	ds_read_b128 v[200:203], v87 offset:16384
	v_exp_f32_e32 v152, v152
	v_exp_f32_e32 v153, v153
	s_waitcnt lgkmcnt(6)
	v_mfma_f32_32x32x16_bf16 v[50:65], v[188:191], v[114:117], v[50:65]
	ds_read_b128 v[204:207], v87 offset:24576
	v_add_f32_e32 v122, v146, v122
	v_add_f32_e32 v123, v147, v123
	v_add_f32_e32 v122, v148, v122
	v_add_f32_e32 v123, v149, v123
	s_waitcnt lgkmcnt(6)
	v_mfma_f32_32x32x16_bf16 v[66:81], v[192:195], v[114:117], v[66:81]
	v_add_f32_e32 v122, v150, v122
	v_add_f32_e32 v123, v151, v123
	v_add_f32_e32 v122, v152, v122
	v_add_f32_e32 v123, v153, v123
	v_cvt_pk_bf16_f32 v118, v146, v147
	v_cvt_pk_bf16_f32 v119, v148, v149
	v_cvt_pk_bf16_f32 v120, v150, v151
	v_cvt_pk_bf16_f32 v121, v152, v153
	v_mfma_f32_32x32x16_bf16 v[138:153], v[98:101], v[10:13], 0
	ds_read_b128 v[98:101], v82 offset:24576
	ds_read_b128 v[128:131], v88 offset:0
	v_exp_f32_e32 v154, v154
	v_exp_f32_e32 v155, v155
	v_mfma_f32_32x32x16_bf16 v[138:153], v[102:105], v[14:17], v[138:153]
	ds_read_b128 v[102:105], v83 offset:24576
	ds_read_b128 v[184:187], v88 offset:8192
	v_exp_f32_e32 v156, v156
	v_exp_f32_e32 v157, v157
	s_waitcnt lgkmcnt(8)
	v_mfma_f32_32x32x16_bf16 v[18:33], v[196:199], v[118:121], v[18:33]
	v_exp_f32_e32 v158, v158
	v_exp_f32_e32 v159, v159
	s_waitcnt lgkmcnt(6)
	v_mfma_f32_32x32x16_bf16 v[34:49], v[216:219], v[118:121], v[34:49]
	ds_read_b128 v[188:191], v88 offset:16384
	v_exp_f32_e32 v160, v160
	v_exp_f32_e32 v161, v161
	s_waitcnt lgkmcnt(6)
	v_mfma_f32_32x32x16_bf16 v[50:65], v[200:203], v[118:121], v[50:65]
	ds_read_b128 v[192:195], v88 offset:24576
	v_add_f32_e32 v122, v154, v122
	v_add_f32_e32 v123, v155, v123
	v_add_f32_e32 v122, v156, v122
	v_add_f32_e32 v123, v157, v123
	s_waitcnt lgkmcnt(6)
	v_mfma_f32_32x32x16_bf16 v[66:81], v[204:207], v[118:121], v[66:81]
	v_add_f32_e32 v122, v158, v122
	v_add_f32_e32 v123, v159, v123
	v_add_f32_e32 v122, v160, v122
	v_add_f32_e32 v123, v161, v123
	v_cvt_pk_bf16_f32 v114, v154, v155
	v_cvt_pk_bf16_f32 v115, v156, v157
	v_cvt_pk_bf16_f32 v116, v158, v159
	v_cvt_pk_bf16_f32 v117, v160, v161
	v_mfma_f32_32x32x16_bf16 v[138:153], v[106:109], v[2:5], v[138:153]
	ds_read_b128 v[106:109], v84 offset:24576
	ds_read_b128 v[196:199], v89 offset:0
	v_exp_f32_e32 v162, v162
	v_exp_f32_e32 v163, v163
	v_mfma_f32_32x32x16_bf16 v[138:153], v[110:113], v[6:9], v[138:153]
	ds_read_b128 v[110:113], v85 offset:24576
	ds_read_b128 v[216:219], v89 offset:8192
	v_exp_f32_e32 v164, v164
	v_exp_f32_e32 v165, v165
	s_waitcnt lgkmcnt(8)
	v_mfma_f32_32x32x16_bf16 v[18:33], v[128:131], v[114:117], v[18:33]
	v_exp_f32_e32 v166, v166
	v_exp_f32_e32 v167, v167
	s_waitcnt lgkmcnt(6)
	v_mfma_f32_32x32x16_bf16 v[34:49], v[184:187], v[114:117], v[34:49]
	ds_read_b128 v[200:203], v89 offset:16384
	v_exp_f32_e32 v168, v168
	v_exp_f32_e32 v169, v169
	s_waitcnt lgkmcnt(6)
	v_mfma_f32_32x32x16_bf16 v[50:65], v[188:191], v[114:117], v[50:65]
	ds_read_b128 v[204:207], v89 offset:24576
	v_add_f32_e32 v122, v162, v122
	v_add_f32_e32 v123, v163, v123
	v_add_f32_e32 v122, v164, v122
	v_add_f32_e32 v123, v165, v123
	s_waitcnt lgkmcnt(6)
	v_mfma_f32_32x32x16_bf16 v[66:81], v[192:195], v[114:117], v[66:81]
	v_add_f32_e32 v122, v166, v122
	v_add_f32_e32 v123, v167, v123
	v_add_f32_e32 v122, v168, v122
	v_add_f32_e32 v123, v169, v123
	v_cvt_pk_bf16_f32 v118, v162, v163
	v_cvt_pk_bf16_f32 v119, v164, v165
	v_cvt_pk_bf16_f32 v120, v166, v167
	v_cvt_pk_bf16_f32 v121, v168, v169
	v_mfma_f32_32x32x16_bf16 v[154:169], v[98:101], v[10:13], 0
	ds_read_b128 v[128:131], v90 offset:0
	v_exp_f32_e32 v138, v138
	v_exp_f32_e32 v139, v139
	v_mfma_f32_32x32x16_bf16 v[154:169], v[102:105], v[14:17], v[154:169]
	ds_read_b128 v[184:187], v90 offset:8192
	v_exp_f32_e32 v140, v140
	v_exp_f32_e32 v141, v141
	s_waitcnt lgkmcnt(6)
	v_mfma_f32_32x32x16_bf16 v[18:33], v[196:199], v[118:121], v[18:33]
	v_exp_f32_e32 v142, v142
	v_exp_f32_e32 v143, v143
	s_waitcnt lgkmcnt(4)
	v_mfma_f32_32x32x16_bf16 v[34:49], v[216:219], v[118:121], v[34:49]
	ds_read_b128 v[188:191], v90 offset:16384
	v_exp_f32_e32 v144, v144
	v_exp_f32_e32 v145, v145
	s_waitcnt lgkmcnt(4)
	v_mfma_f32_32x32x16_bf16 v[50:65], v[200:203], v[118:121], v[50:65]
	ds_read_b128 v[192:195], v90 offset:24576
	v_add_f32_e32 v122, v138, v122
	v_add_f32_e32 v123, v139, v123
	v_add_f32_e32 v122, v140, v122
	v_add_f32_e32 v123, v141, v123
	s_waitcnt lgkmcnt(4)
	v_mfma_f32_32x32x16_bf16 v[66:81], v[204:207], v[118:121], v[66:81]
	v_add_f32_e32 v122, v142, v122
	v_add_f32_e32 v123, v143, v123
	v_add_f32_e32 v122, v144, v122
	v_add_f32_e32 v123, v145, v123
	v_cvt_pk_bf16_f32 v114, v138, v139
	v_cvt_pk_bf16_f32 v115, v140, v141
	v_cvt_pk_bf16_f32 v116, v142, v143
	v_cvt_pk_bf16_f32 v117, v144, v145
	v_mfma_f32_32x32x16_bf16 v[154:169], v[106:109], v[2:5], v[154:169]
	ds_read_b128 v[196:199], v91 offset:0
	v_exp_f32_e32 v146, v146
	v_exp_f32_e32 v147, v147
	v_mfma_f32_32x32x16_bf16 v[154:169], v[110:113], v[6:9], v[154:169]
	ds_read_b128 v[216:219], v91 offset:8192
	v_exp_f32_e32 v148, v148
	v_exp_f32_e32 v149, v149
	s_waitcnt lgkmcnt(5)
	v_mfma_f32_32x32x16_bf16 v[18:33], v[128:131], v[114:117], v[18:33]
	v_exp_f32_e32 v150, v150
	v_exp_f32_e32 v151, v151
	s_waitcnt lgkmcnt(4)
	v_mfma_f32_32x32x16_bf16 v[34:49], v[184:187], v[114:117], v[34:49]
	ds_read_b128 v[200:203], v91 offset:16384
	v_exp_f32_e32 v152, v152
	v_exp_f32_e32 v153, v153
	s_waitcnt lgkmcnt(4)
	v_mfma_f32_32x32x16_bf16 v[50:65], v[188:191], v[114:117], v[50:65]
	ds_read_b128 v[204:207], v91 offset:24576
	v_add_f32_e32 v122, v146, v122
	v_add_f32_e32 v123, v147, v123
	v_add_f32_e32 v122, v148, v122
	v_add_f32_e32 v123, v149, v123
	s_waitcnt lgkmcnt(4)
	v_mfma_f32_32x32x16_bf16 v[66:81], v[192:195], v[114:117], v[66:81]
	v_add_f32_e32 v122, v150, v122
	v_add_f32_e32 v123, v151, v123
	v_add_f32_e32 v122, v152, v122
	v_add_f32_e32 v123, v153, v123
	v_cvt_pk_bf16_f32 v118, v146, v147
	v_cvt_pk_bf16_f32 v119, v148, v149
	v_cvt_pk_bf16_f32 v120, v150, v151
	v_cvt_pk_bf16_f32 v121, v152, v153
	s_waitcnt lgkmcnt(3)
	s_nop 0
	v_mfma_f32_32x32x16_bf16 v[18:33], v[196:199], v[118:121], v[18:33]
	ds_read_b128 v[128:131], v92 offset:0
	v_exp_f32_e32 v154, v154
	v_exp_f32_e32 v155, v155
	v_exp_f32_e32 v156, v156
	s_waitcnt lgkmcnt(3)
	v_mfma_f32_32x32x16_bf16 v[34:49], v[216:219], v[118:121], v[34:49]
	ds_read_b128 v[184:187], v92 offset:8192
	v_exp_f32_e32 v157, v157
	v_exp_f32_e32 v158, v158
	v_exp_f32_e32 v159, v159
	s_waitcnt lgkmcnt(3)
	v_mfma_f32_32x32x16_bf16 v[50:65], v[200:203], v[118:121], v[50:65]
	ds_read_b128 v[188:191], v92 offset:16384
	v_exp_f32_e32 v160, v160
	v_exp_f32_e32 v161, v161
	v_add_f32_e32 v122, v154, v122
	v_add_f32_e32 v123, v155, v123
	s_waitcnt lgkmcnt(3)
	v_mfma_f32_32x32x16_bf16 v[66:81], v[204:207], v[118:121], v[66:81]
	ds_read_b128 v[192:195], v92 offset:24576
	v_add_f32_e32 v122, v156, v122
	v_add_f32_e32 v123, v157, v123
	v_add_f32_e32 v122, v158, v122
	v_add_f32_e32 v123, v159, v123
	v_add_f32_e32 v122, v160, v122
	v_add_f32_e32 v123, v161, v123
	v_cvt_pk_bf16_f32 v114, v154, v155
	v_cvt_pk_bf16_f32 v115, v156, v157
	v_cvt_pk_bf16_f32 v116, v158, v159
	v_cvt_pk_bf16_f32 v117, v160, v161
	s_waitcnt lgkmcnt(3)
	s_nop 0
	v_mfma_f32_32x32x16_bf16 v[18:33], v[128:131], v[114:117], v[18:33]
	ds_read_b128 v[196:199], v93 offset:0
	v_exp_f32_e32 v162, v162
	v_exp_f32_e32 v163, v163
	v_exp_f32_e32 v164, v164
	s_waitcnt lgkmcnt(3)
	v_mfma_f32_32x32x16_bf16 v[34:49], v[184:187], v[114:117], v[34:49]
	ds_read_b128 v[216:219], v93 offset:8192
	v_exp_f32_e32 v165, v165
	v_exp_f32_e32 v166, v166
	v_exp_f32_e32 v167, v167
	s_waitcnt lgkmcnt(3)
	v_mfma_f32_32x32x16_bf16 v[50:65], v[188:191], v[114:117], v[50:65]
	ds_read_b128 v[200:203], v93 offset:16384
	v_exp_f32_e32 v168, v168
	v_exp_f32_e32 v169, v169
	v_add_f32_e32 v122, v162, v122
	v_add_f32_e32 v123, v163, v123
	s_waitcnt lgkmcnt(3)
	v_mfma_f32_32x32x16_bf16 v[66:81], v[192:195], v[114:117], v[66:81]
	ds_read_b128 v[204:207], v93 offset:24576
	v_add_f32_e32 v122, v164, v122
	v_add_f32_e32 v123, v165, v123
	v_add_f32_e32 v122, v166, v122
	v_add_f32_e32 v123, v167, v123
	v_add_f32_e32 v122, v168, v122
	v_add_f32_e32 v123, v169, v123
	v_cvt_pk_bf16_f32 v118, v162, v163
	v_cvt_pk_bf16_f32 v119, v164, v165
	v_cvt_pk_bf16_f32 v120, v166, v167
	v_cvt_pk_bf16_f32 v121, v168, v169
	s_waitcnt lgkmcnt(3)
	s_nop 0
	v_mfma_f32_32x32x16_bf16 v[18:33], v[196:199], v[118:121], v[18:33]
	s_waitcnt lgkmcnt(2)
	v_mfma_f32_32x32x16_bf16 v[34:49], v[216:219], v[118:121], v[34:49]
	s_waitcnt lgkmcnt(1)
	v_mfma_f32_32x32x16_bf16 v[50:65], v[200:203], v[118:121], v[50:65]
	s_waitcnt lgkmcnt(0)
	v_mfma_f32_32x32x16_bf16 v[66:81], v[204:207], v[118:121], v[66:81]
	s_waitcnt vmcnt(0)
	s_waitcnt lgkmcnt(0)
	s_barrier
	v_readlane_b32 s64, v175, 0
	v_readlane_b32 s65, v175, 1
	v_readlane_b32 s66, v175, 2
	v_readlane_b32 s67, v175, 3
	v_readlane_b32 s68, v175, 4
	v_readlane_b32 s69, v175, 5
	v_readlane_b32 s70, v175, 6
	v_readlane_b32 s71, v175, 7
	v_readlane_b32 s72, v175, 8
	v_readlane_b32 s73, v175, 9
	v_readlane_b32 s74, v175, 10
	v_readlane_b32 s75, v175, 11
	v_readlane_b32 s76, v175, 12
	v_readlane_b32 s77, v175, 13
	v_readlane_b32 s78, v175, 14
	v_readlane_b32 s79, v175, 15
	s_nop 4
	s_mov_b32 s10, 0x3fb8aa3b
	s_mov_b32 s11, 0xc2ce8ed0
	s_mov_b32 s6, 0x42b17218
	v_cmp_eq_u32_e64 s[40:41], 0, v179
	s_lshl_b32 s30, s14, 1
	v_lshlrev_b32_e32 v196, 3, v178
	v_mov_b32_e32 v197, 0
	v_lshlrev_b32_e32 v198, 4, v179
	v_or3_b32 v198, v198, v177, v180
	v_ashrrev_i32_e32 v199, 31, v198
	v_lshlrev_b64 v[198:199], 11, v[198:199]
	s_mov_b64 s[100:101], 0x18a10000
	v_lshl_add_u64 v[198:199], s[42:43], 0, v[198:199]
	v_lshl_add_u64 v[198:199], v[198:199], 0, s[30:31]
	v_lshl_add_u64 v[198:199], v[198:199], 0, v[196:197]
	v_lshl_add_u64 v[198:199], v[198:199], 0, s[100:101]
	global_load_dwordx2 v[146:147], v[198:199], off
	global_load_dwordx2 v[148:149], v[198:199], off offset:32
	global_load_dwordx2 v[150:151], v[198:199], off offset:64
	global_load_dwordx2 v[152:153], v[198:199], off offset:96
	global_load_dwordx2 v[188:189], v[198:199], off offset:128
	global_load_dwordx2 v[190:191], v[198:199], off offset:160
	global_load_dwordx2 v[192:193], v[198:199], off offset:192
	global_load_dwordx2 v[194:195], v[198:199], off offset:224
	s_mov_b64 s[100:101], exec
	s_and_b64 exec, exec, s[4:5]
	s_cbranch_execz .Lpop_skip
	v_readlane_b32 s14, v255, 22
	v_readlane_b32 s15, v255, 23
	v_mov_b32_e32 v224, 1
	s_nop 4
	global_atomic_add v224, v0, v224, s[14:15] sc0
.Lpop_skip:
	s_mov_b64 exec, s[100:101]
	v_mov_b32_e32 v235, 1
	s_load_dwordx2 s[100:101], s[44:45], 0x80
	v_readlane_b32 s14, v255, 36
	v_readlane_b32 s15, v255, 37
	s_nop 3
	s_lshl_b64 s[14:15], s[14:15], 2
	s_waitcnt lgkmcnt(0)
	v_add_f32_e32 v122, v123, v122
	v_readlane_b32 s6, v255, 46
	v_readlane_b32 s10, v255, 45
	s_nop 3
	s_cmp_eq_u32 s6, 0
	s_cbranch_scc0 .Lattn_lam_have
	v_readlane_b32 s6, v255, 20
	s_nop 3
	v_or_b32_e32 v90, s6, v181
	v_lshlrev_b32_e32 v90, 2, v90
	s_load_dwordx2 s[10:11], s[44:45], 0x60
	s_waitcnt lgkmcnt(0)
	global_load_dword v91, v90, s[10:11]
	s_load_dwordx2 s[10:11], s[44:45], 0x68
	s_waitcnt lgkmcnt(0)
	global_load_dword v92, v90, s[10:11]
	s_load_dwordx2 s[10:11], s[44:45], 0x70
	s_waitcnt lgkmcnt(0)
	global_load_dword v93, v90, s[10:11]
	s_load_dwordx2 s[10:11], s[44:45], 0x78
	s_waitcnt lgkmcnt(0)
	global_load_dword v94, v90, s[10:11]
	s_waitcnt vmcnt(0)
	v_mul_f32_e32 v91, v91, v92
	v_mul_f32_e32 v93, v93, v94
	v_xor_b32_e32 v90, 1, v223
	v_lshlrev_b32_e32 v90, 2, v90
	ds_bpermute_b32 v92, v90, v91
	ds_bpermute_b32 v94, v90, v93
	s_waitcnt lgkmcnt(0)
	v_add_f32_e32 v91, v91, v92
	v_add_f32_e32 v93, v93, v94
	v_xor_b32_e32 v90, 2, v223
	v_lshlrev_b32_e32 v90, 2, v90
	ds_bpermute_b32 v92, v90, v91
	ds_bpermute_b32 v94, v90, v93
	s_waitcnt lgkmcnt(0)
	v_add_f32_e32 v91, v91, v92
	v_add_f32_e32 v93, v93, v94
	v_xor_b32_e32 v90, 4, v223
	v_lshlrev_b32_e32 v90, 2, v90
	ds_bpermute_b32 v92, v90, v91
	ds_bpermute_b32 v94, v90, v93
	s_waitcnt lgkmcnt(0)
	v_add_f32_e32 v91, v91, v92
	v_add_f32_e32 v93, v93, v94
	v_xor_b32_e32 v90, 8, v223
	v_lshlrev_b32_e32 v90, 2, v90
	ds_bpermute_b32 v92, v90, v91
	ds_bpermute_b32 v94, v90, v93
	s_waitcnt lgkmcnt(0)
	v_add_f32_e32 v91, v91, v92
	v_add_f32_e32 v93, v93, v94
	v_xor_b32_e32 v90, 16, v223
	v_lshlrev_b32_e32 v90, 2, v90
	ds_bpermute_b32 v92, v90, v91
	ds_bpermute_b32 v94, v90, v93
	s_waitcnt lgkmcnt(0)
	v_add_f32_e32 v91, v91, v92
	v_add_f32_e32 v93, v93, v94
	v_xor_b32_e32 v90, 32, v223
	v_lshlrev_b32_e32 v90, 2, v90
	ds_bpermute_b32 v92, v90, v91
	ds_bpermute_b32 v94, v90, v93
	s_waitcnt lgkmcnt(0)
	v_add_f32_e32 v91, v91, v92
	v_add_f32_e32 v93, v93, v94
	s_mov_b32 s10, 0x3fb8aa3b
	s_mov_b32 s11, 0xc2ce8ed0
	s_mov_b32 s6, 0x42b17218
	v_mul_f32_e32 v85, 0x3fb8aa3b, v91
	v_fma_f32 v86, v91, s10, -v85
	v_rndne_f32_e32 v87, v85
	v_fmac_f32_e32 v86, 0x32a5705f, v91
	v_sub_f32_e32 v85, v85, v87
	v_add_f32_e32 v85, v85, v86
	v_exp_f32_e32 v85, v85
	v_cvt_i32_f32_e32 v86, v87
	v_cmp_ngt_f32_e32 vcc, s11, v91
	s_nop 0
	v_ldexp_f32 v85, v85, v86
	s_nop 1
	v_cndmask_b32_e32 v85, 0, v85, vcc
	v_cmp_nlt_f32_e32 vcc, s6, v91
	s_nop 1
	v_cndmask_b32_e32 v88, v220, v85, vcc
	v_mul_f32_e32 v85, 0x3fb8aa3b, v93
	v_fma_f32 v86, v93, s10, -v85
	v_rndne_f32_e32 v87, v85
	v_fmac_f32_e32 v86, 0x32a5705f, v93
	v_sub_f32_e32 v85, v85, v87
	v_add_f32_e32 v85, v85, v86
	v_exp_f32_e32 v85, v85
	v_cvt_i32_f32_e32 v86, v87
	v_cmp_ngt_f32_e32 vcc, s11, v93
	s_nop 0
	v_ldexp_f32 v85, v85, v86
	s_nop 1
	v_cndmask_b32_e32 v85, 0, v85, vcc
	v_cmp_nlt_f32_e32 vcc, s6, v93
	s_nop 1
	v_cndmask_b32_e32 v89, v220, v85, vcc
	v_sub_f32_e32 v88, v88, v89
	v_add_f32_e32 v88, v236, v88
	s_nop 0
	v_readfirstlane_b32 s10, v88
	s_mov_b32 s6, 1
	s_nop 3
	v_writelane_b32 v255, s10, 45
	v_writelane_b32 v255, s6, 46
